# weight-conversion items rebalanced in P2: three-gate-tile workgroups convert one item per wave instead of two, the two-gate-tile and HGRN workgroups one more each
# speedup vs baseline: 1.0090x; 1.0034x over previous
;     ...
;     { int it = (PART == 0 ? gw : I_IN + gw); const int end = (PART == 0 ? I_IN : (I_IN + it_last < NITEMS ? I_IN + it_last : NITEMS));
;       if (it < end) {
; __global__ void __launch_bounds__(NTHREADS, 2) hybrid_fwd(Args args) {
;     ...
;                 if (idx < 128) attn_mfma(args, idx * 40 + wave, 5, NWAVES); else attn_mfma(args, 5120 + (idx - 128) * 48 + wave, 6, NWAVES);
;                 if (idx < 128) p0_prologue<1>(args, lds, wave, lane, idx * NWAVES + wave, 1024, 2048);
;                 else p0_prologue<1>(args, lds, wave, lane, 2048 + (idx - 128) * NWAVES + wave, 1024);
;                 S.l0 = idx; S.l1 = 192 + idx; S.l2 = idx < 128 ? 384 + idx : -1; }
.LBB0_416:
	s_mov_b64 s[2:3], -1
	s_and_b64 vcc, exec, s[0:1]
	s_cbranch_vccz .LBB0_511
	s_lshl_b32 s0, s33, 3
	v_readlane_b32 s1, v254, 11
	s_add_i32 s0, s0, s1
	s_addk_i32 s0, 0xfe00
	s_cmpk_gt_i32 s0, 0x167f
	s_cbranch_scc1 .LBB0_510
	s_add_i32 s40, s0, 0x1200
	s_cmp_gt_i32 s0, -1
	s_cbranch_scc0 .LBB0_425
	s_cmpk_gt_u32 s40, 0x13ff
	s_cbranch_scc0 .LBB0_426
	s_cmpk_gt_u32 s40, 0x15ff
	s_cbranch_scc0 .LBB0_427
	s_cmpk_gt_u32 s40, 0x17ff
	s_cbranch_scc0 .LBB0_428
	s_cmpk_gt_u32 s40, 0x22ff
	s_cbranch_scc0 .LBB0_429
	s_add_u32 s8, s72, 0x2500000
	s_addc_u32 s9, s73, 0
	s_lshl_b32 s0, s40, 1
	s_add_i32 s0, s0, 0x7fffba00
	s_and_b32 s4, s0, 0x7fffffc0
	s_lshl_b32 s0, s40, 5
	s_and_b32 s10, s0, 0x3e0
	s_mov_b64 s[6:7], 0
	s_mov_b64 s[0:1], 0
	s_mov_b64 s[2:3], s[68:69]
	s_branch .LBB0_430

; __device__ __forceinline__ ConvItem conv_item(const Args& a, unsigned char* ws, int it) {
;     ...
;     if (r < I_IN) { const int nblk = INW / 32, kb = r / nblk, nb = r % nblk, n0d = 32 * nb; const int sec = n0d >> 10; int n0s = n0d;
;         if (sec == 4 || sec == 5) { const int q = n0d & 255; n0s = (n0d - q) + 64 * ((q >> 5) & 3) + 32 * (q >> 7); }
;         p.W = a.in[2]; p.N = INW; p.WT = (bf16*)(ws + WS_WIN); p.ldT = 1024; p.k0 = 64 * kb; p.n0d = n0d; p.n0s = n0s; if (sec == 1 || sec == 3 || sec >= 7) p.cs = -1.4426950408889634f; return p; } r -= I_IN;
;     if (r < I_SQ) { p.W = a.in[7]; p.N = 1024; p.WT = (bf16*)(ws + WS_WHS); p.ldT = 2048; p.k0 = 64 * (r / 32); p.n0d = p.n0s = 32 * (r % 32); return p; } r -= I_SQ;
;     if (r < I_SQ) { p.W = a.in[8]; p.N = 1024; p.WT = (bf16*)(ws + WS_WHS); p.ldT = 2048; p.koff = 1024; p.k0 = 64 * (r / 32); p.n0d = p.n0s = 32 * (r % 32); return p; } r -= I_SQ;
;     if (r < I_SQ) { p.W = a.in[9]; p.N = 1024; p.WT = (bf16*)(ws + WS_WO); p.ldT = 1024; p.k0 = 64 * (r / 32); p.n0d = p.n0s = 32 * (r % 32); return p; } r -= I_SQ;
;     if (r < I_F1) { const int nblk = 2 * FFH / 32, kb = r / nblk, nb = r % nblk, n0d = 32 * nb, pn = n0d >> 8, q = n0d & 255;
;         p.W = a.in[11]; p.N = 2 * FFH; p.WT = (bf16*)(ws + WS_WF1); p.ldT = 1024; p.k0 = 64 * kb; p.n0d = n0d; p.n0s = (q >> 7) * FFH + 128 * pn + (q & 127); p.ks = a.in[10]; return p; } r -= I_F1;
;     p.W = a.in[12]; p.N = 1024; p.WT = (bf16*)(ws + WS_WF2); p.ldT = FFH; p.k0 = 64 * (r / 32); p.n0d = p.n0s = 32 * (r % 32); return p;
;     ...
;             const bool hb = it + NGW < end; if (hb) { pb = conv_item(a, ws, it + NGW); conv_load(pb, wb, kb, lane); }
;             conv_finish(pa, wa, ka, scr, lane);
;             if (!hb) break; it += NGW;
;             const bool ha = it + NGW < end; if (ha) { pa = conv_item(a, ws, it + NGW); conv_load(pa, wa, ka, lane); }
.LBB0_534:
	s_cmpk_lt_i32 s18, 0
	s_cselect_b64 s[12:13], -1, 0
	s_cmpk_gt_i32 s18, 0xffff
	s_mov_b64 s[4:5], s[2:3]
	s_mov_b32 s10, s21
	s_mov_b32 s11, s0
	s_mov_b32 s8, s6
	s_mov_b32 s22, s20
	s_cbranch_scc1 .LBB0_544
	s_add_i32 s1, s18, 0x1600
	s_and_b64 vcc, exec, s[14:15]
	s_cbranch_vccz .LBB0_537
	s_add_u32 s4, s72, 0x1a00000
	s_addc_u32 s5, s73, 0
	s_add_i32 s7, s1, 0xe800
	s_and_b32 s8, s7, 0xffff
	s_mul_i32 s8, s8, 0xba2f
	s_lshr_b32 s8, s8, 23
	s_mul_i32 s9, s8, 0xb0
	s_sub_i32 s7, s7, s9
	s_and_b32 s9, s7, 0xffff
	s_lshl_b32 s22, s9, 5
	s_bfe_i32 s7, s7, 0x10002
	s_lshl_b32 s9, s9, 4
	s_and_b32 s7, s7, 0xb00
	s_and_b32 s9, s9, 0xf80
	v_readlane_b32 s24, v254, 0
	s_add_i32 s7, s7, s9
	s_and_b32 s9, s22, 0x60
	v_readlane_b32 s28, v254, 4
	v_readlane_b32 s29, v254, 5
	v_readlane_b32 s30, v254, 6
	v_readlane_b32 s31, v254, 7
	s_lshl_b32 s8, s8, 6
	s_or_b32 s10, s7, s9
	s_mov_b64 s[18:19], 0
	v_readlane_b32 s25, v254, 1
	v_readlane_b32 s26, v254, 2
	v_readlane_b32 s27, v254, 3
	s_mov_b64 s[14:15], s[28:29]
	s_mov_b64 s[16:17], s[30:31]
	s_branch .LBB0_538

;     ...
;     { int it = (PART == 0 ? gw : I_IN + gw); const int end = (PART == 0 ? I_IN : (I_IN + it_last < NITEMS ? I_IN + it_last : NITEMS));
;       if (it < end) {
; __global__ void __launch_bounds__(NTHREADS, 2) hybrid_fwd(Args args) {
;     ...
;             if ((int)blockIdx.x < 64) { hgrn_v2(args, lds, (int)blockIdx.x, 64); p0_prologue<1>(args, lds, wave, lane, 2048 + 512 + (int)blockIdx.x * NWAVES + wave, 1024); S.l0 = -1; S.l1 = -1; S.l2 = -1; }
.LBB0_580:
	s_lshl_b32 s0, s33, 3
	v_readlane_b32 s1, v254, 11
	s_add_i32 s0, s0, s1
	s_addk_i32 s0, 0x600
	s_cmpk_gt_i32 s0, 0x167f
	s_cbranch_scc1 .LBB0_666
	s_add_i32 s38, s0, 0x1200
	s_cmp_gt_i32 s0, -1
	s_cbranch_scc0 .LBB0_587
	s_cmpk_gt_u32 s38, 0x13ff
	s_cbranch_scc0 .LBB0_588
	s_cmpk_gt_u32 s38, 0x15ff
	s_cbranch_scc0 .LBB0_589
	s_cmpk_gt_u32 s38, 0x17ff
	s_cbranch_scc0 .LBB0_590
	s_cmpk_gt_u32 s38, 0x22ff
	s_cbranch_scc0 .LBB0_591
	s_add_u32 s8, s72, 0x2500000
	s_addc_u32 s9, s73, 0
	s_lshl_b32 s0, s38, 1
	s_add_i32 s0, s0, 0x7fffba00
	s_and_b32 s4, s0, 0x7fffffc0
	s_lshl_b32 s0, s38, 5
	s_and_b32 s10, s0, 0x3e0
	s_mov_b64 s[6:7], 0
	s_mov_b64 s[0:1], 0
	s_mov_b64 s[2:3], s[68:69]
	s_branch .LBB0_592
